# mLSTM: counted wait vmcnt(1) at loop top (h store of previous chunk stays in flight)
# speedup vs baseline: 1.0081x; 1.0081x over previous
; #define LAS __attribute__((address_space(3)))
; __device__ __forceinline__ void mlstm_item(const Args& a, LAS unsigned char* L, bool sample, int b, int hh, int sl, bool dry = false) {
;     ...
;     PREFETCH(0);
;     ...
;     for (int c = 0; c < nchunks; ++c) {
; #pragma unroll
;         for (int i = 0; i < 2; ++i) { *(LAS u32x4*)(L + L_QS + (prow + 16 * i) * 528 + pcc * 16) = qreg[i]; *(LAS u32x4*)(L + L_KS + (prow + 16 * i) * 528 + pcc * 16) = kreg[i]; }
.Ldma_skip_pro:
	s_waitcnt vmcnt(0)
	s_branch .LBB0_662

; #define LAS __attribute__((address_space(3)))
; __device__ __forceinline__ float bf2f(unsigned b) { return __uint_as_float(b << 16); }
; __device__ __forceinline__ unsigned pk2(float lo, float hi) { unsigned r; asm("v_cvt_pk_bf16_f32 %0, %1, %2" : "=v"(r) : "v"(lo), "v"(hi)); return r; }
; __device__ __forceinline__ void mlstm_item(const Args& a, LAS unsigned char* L, bool sample, int b, int hh, int sl, bool dry = false) {
;     ...
;     for (int c = 0; c < nchunks; ++c) {
; #pragma unroll
;         for (int i = 0; i < 2; ++i) { *(LAS u32x4*)(L + L_QS + (prow + 16 * i) * 528 + pcc * 16) = qreg[i]; *(LAS u32x4*)(L + L_KS + (prow + 16 * i) * 528 + pcc * 16) = kreg[i]; }
;         if (tid < 256) {
;             const float wL0 = GWL[c * 32 + 2 * sp], wL1 = GWL[c * 32 + 2 * sp + 1];
;             const unsigned r0w[2] = {vreg0.x, vreg0.y}, r1w[2] = {vreg1.x, vreg1.y};
; #pragma unroll
;             for (int i = 0; i < 4; ++i) { const unsigned e0 = (i & 1) ? (r0w[i >> 1] >> 16) : (r0w[i >> 1] & 0xffffu), e1 = (i & 1) ? (r1w[i >> 1] >> 16) : (r1w[i >> 1] & 0xffffu);
;                 *(LAS unsigned*)(L + L_VT + (vq * 4 + i) * 80 + sp * 4) = e0 | (e1 << 16);
;                 *(LAS unsigned*)(L + L_VTW + (vq * 4 + i) * 80 + sp * 4) = pk2(bf2f(e0) * wL0, bf2f(e1) * wL1); }
;             if (tid < 16) *(LAS unsigned*)(L + L_VTW + 64 * 80 + sp * 4) = pk2(wL0, wL1);
;         }
.LBB0_662:
	s_waitcnt vmcnt(1)
	s_and_saveexec_b64 s[72:73], s[0:1]
	s_cbranch_execz .LBB0_665
	v_add_u32_e32 v0, 0, v114
	v_add_u32_e32 v0, 0x1c500, v0
	ds_read_b64 v[0:1], v0
	v_lshlrev_b32_e32 v2, 16, v64
	v_lshlrev_b32_e32 v4, 16, v62
	v_and_or_b32 v5, v62, s88, v2
	v_add_u32_e32 v3, v106, v108
	s_waitcnt lgkmcnt(0)
	v_mul_f32_e32 v4, v0, v4
	v_mul_f32_e32 v2, v1, v2
	v_cvt_pk_bf16_f32 v2, v4, v2
	v_and_b32_e32 v4, 0xffff0000, v64
	v_or_b32_sdwa v6, v4, v62 dst_sel:DWORD dst_unused:UNUSED_PAD src0_sel:DWORD src1_sel:WORD_1
	v_add_u32_e32 v7, 0x8400, v3
	ds_write2_b32 v7, v5, v6 offset1:20
	v_and_b32_e32 v5, 0xffff0000, v62
	v_mul_f32_e32 v5, v0, v5
	v_mul_f32_e32 v4, v1, v4
	v_add_u32_e32 v3, 0x9c00, v3
	v_cvt_pk_bf16_f32 v4, v5, v4
	ds_write2_b32 v3, v2, v4 offset0:64 offset1:84
	v_lshlrev_b32_e32 v2, 16, v65
	v_lshlrev_b32_e32 v5, 16, v63
	v_and_or_b32 v4, v63, s88, v2
	v_mul_f32_e32 v5, v0, v5
	v_mul_f32_e32 v2, v1, v2
	v_cvt_pk_bf16_f32 v2, v5, v2
	v_and_b32_e32 v5, 0xffff0000, v65
	v_or_b32_sdwa v6, v5, v63 dst_sel:DWORD dst_unused:UNUSED_PAD src0_sel:DWORD src1_sel:WORD_1
	ds_write2_b32 v7, v4, v6 offset0:40 offset1:60
	v_and_b32_e32 v4, 0xffff0000, v63
	v_mul_f32_e32 v4, v0, v4
	v_mul_f32_e32 v5, v1, v5
	v_cvt_pk_bf16_f32 v4, v4, v5
	ds_write2_b32 v3, v2, v4 offset0:104 offset1:124
	s_and_b64 exec, exec, s[14:15]
	s_cbranch_execz .LBB0_665
	v_cvt_pk_bf16_f32 v0, v0, v1
	ds_write_b32 v106, v0 offset:45312

; #define LAS __attribute__((address_space(3)))
; __device__ __forceinline__ float bf2f(unsigned b) { return __uint_as_float(b << 16); }
; __device__ __forceinline__ unsigned pk2(float lo, float hi) { unsigned r; asm("v_cvt_pk_bf16_f32 %0, %1, %2" : "=v"(r) : "v"(lo), "v"(hi)); return r; }
; __device__ __forceinline__ void mlstm_item(const Args& a, LAS unsigned char* L, bool sample, int b, int hh, int sl, bool dry = false) {
;     ...
;     for (int c = 0; c < nchunks; ++c) {
; #pragma unroll
;         for (int i = 0; i < 2; ++i) { *(LAS u32x4*)(L + L_QS + (prow + 16 * i) * 528 + pcc * 16) = qreg[i]; *(LAS u32x4*)(L + L_KS + (prow + 16 * i) * 528 + pcc * 16) = kreg[i]; }
;         if (tid < 256) {
;             const float wL0 = GWL[c * 32 + 2 * sp], wL1 = GWL[c * 32 + 2 * sp + 1];
;             const unsigned r0w[2] = {vreg0.x, vreg0.y}, r1w[2] = {vreg1.x, vreg1.y};
; #pragma unroll
;             for (int i = 0; i < 4; ++i) { const unsigned e0 = (i & 1) ? (r0w[i >> 1] >> 16) : (r0w[i >> 1] & 0xffffu), e1 = (i & 1) ? (r1w[i >> 1] >> 16) : (r1w[i >> 1] & 0xffffu);
;                 *(LAS unsigned*)(L + L_VT + (vq * 4 + i) * 80 + sp * 4) = e0 | (e1 << 16);
;                 *(LAS unsigned*)(L + L_VTW + (vq * 4 + i) * 80 + sp * 4) = pk2(bf2f(e0) * wL0, bf2f(e1) * wL1); }
;             if (tid < 16) *(LAS unsigned*)(L + L_VTW + 64 * 80 + sp * 4) = pk2(wL0, wL1);
;         }
.LBB0_676:
	s_waitcnt vmcnt(1)
	s_and_saveexec_b64 s[70:71], s[0:1]
	s_cbranch_execz .LBB0_679
	s_add_i32 s0, 0, 0x1c500
	v_add_u32_e32 v0, s0, v107
	ds_read_b64 v[0:1], v0 offset:8064
	v_lshlrev_b32_e32 v2, 16, v64
	v_lshlrev_b32_e32 v4, 16, v62
	v_and_or_b32 v5, v62, s88, v2
	v_add_u32_e32 v3, v106, v108
	s_waitcnt lgkmcnt(0)
	v_mul_f32_e32 v4, v0, v4
	v_mul_f32_e32 v2, v1, v2
	v_cvt_pk_bf16_f32 v2, v4, v2
	v_and_b32_e32 v4, 0xffff0000, v64
	v_or_b32_sdwa v6, v4, v62 dst_sel:DWORD dst_unused:UNUSED_PAD src0_sel:DWORD src1_sel:WORD_1
	v_add_u32_e32 v7, 0x8400, v3
	ds_write2_b32 v7, v5, v6 offset1:20
	v_and_b32_e32 v5, 0xffff0000, v62
	v_mul_f32_e32 v5, v0, v5
	v_mul_f32_e32 v4, v1, v4
	v_add_u32_e32 v3, 0x9c00, v3
	v_cvt_pk_bf16_f32 v4, v5, v4
	ds_write2_b32 v3, v2, v4 offset0:64 offset1:84
	v_lshlrev_b32_e32 v2, 16, v65
	v_lshlrev_b32_e32 v5, 16, v63
	v_and_or_b32 v4, v63, s88, v2
	v_mul_f32_e32 v5, v0, v5
	v_mul_f32_e32 v2, v1, v2
	v_cvt_pk_bf16_f32 v2, v5, v2
	v_and_b32_e32 v5, 0xffff0000, v65
	v_or_b32_sdwa v6, v5, v63 dst_sel:DWORD dst_unused:UNUSED_PAD src0_sel:DWORD src1_sel:WORD_1
	ds_write2_b32 v7, v4, v6 offset0:40 offset1:60
	v_and_b32_e32 v4, 0xffff0000, v63
	v_mul_f32_e32 v4, v0, v4
	v_mul_f32_e32 v5, v1, v5
	v_cvt_pk_bf16_f32 v4, v4, v5
	ds_write2_b32 v3, v2, v4 offset0:104 offset1:124
	s_and_b64 exec, exec, s[14:15]
	s_cbranch_execz .LBB0_679
	v_cvt_pk_bf16_f32 v0, v0, v1
	ds_write_b32 v106, v0 offset:45312
